# v102 + static s_setprio 1 for waves 4-7 in the E2 banded-attention tile loop
# baseline (speedup 1.0000x reference)
.LBB0_398:
	s_waitcnt vmcnt(6)
	ds_write_b32 v15, v3
	v_lshlrev_b32_e32 v125, 2, v13
	v_lshrrev_b32_e32 v0, 2, v2
	v_and_or_b32 v0, v0, 3, v125
	v_mul_u32_u24_e32 v142, 0xc0, v0
	v_and_b32_e32 v0, 16, v2
	v_lshlrev_b32_e32 v2, 2, v2
	v_and_or_b32 v0, v2, 12, v0
	v_cmp_gt_u32_e64 s[36:37], 32, v14
	v_lshlrev_b32_e32 v144, 1, v0
	v_mov_b32_e32 v14, v1
	v_cndmask_b32_e64 v0, 0, 1.0, s[36:37]
	v_cndmask_b32_e64 v143, v0, 0, s[16:17]
	v_lshlrev_b32_e32 v0, 2, v12
	v_lshl_or_b32 v0, s31, 7, v0
	v_sub_u32_e32 v0, v0, v124
	v_mov_b32_e32 v15, v1
	s_waitcnt vmcnt(0)
	v_mul_u32_u24_e32 v141, 0xd0, v12
	s_min_u32 s8, s34, 2
	v_add_u32_e32 v145, 0, v0
	v_mov_b32_e32 v226, 0
	v_mov_b32_e32 v227, 0
	v_mov_b32_e32 v228, 0
	v_mov_b32_e32 v229, 0
	v_mov_b32_e32 v230, 0
	v_mov_b32_e32 v231, 0
	v_mov_b32_e32 v232, 0
	v_mov_b32_e32 v233, 0
	v_mov_b32_e32 v234, 0
	v_mov_b32_e32 v235, 0
	v_mov_b32_e32 v236, 0
	v_mov_b32_e32 v237, 0
	v_mov_b32_e32 v238, 0
	v_mov_b32_e32 v239, 0
	v_mov_b32_e32 v240, 0
	v_mov_b32_e32 v241, 0
	v_mov_b32_e32 v242, 0
	v_mov_b32_e32 v243, 0
	v_mov_b32_e32 v244, 0
	v_mov_b32_e32 v245, 0
	v_mov_b32_e32 v246, 0
	v_mov_b32_e32 v247, 0
	v_mov_b32_e32 v248, 0
	v_mov_b32_e32 v249, 0
	v_mov_b32_e32 v166, 0
	v_mov_b32_e32 v167, 0
	v_mov_b32_e32 v168, 0
	v_mov_b32_e32 v169, 0
	v_mov_b32_e32 v170, 0
	v_mov_b32_e32 v171, 0
	v_mov_b32_e32 v172, 0
	v_mov_b32_e32 v173, 0
	v_mov_b32_e32 v0, v1
	v_mov_b32_e32 v2, v1
	v_mov_b32_e32 v3, v1
	v_mov_b32_e32 v4, v1
	v_mov_b32_e32 v5, v1
	v_mov_b32_e32 v6, v1
	v_mov_b32_e32 v7, v1
	v_mov_b32_e32 v8, v1
	v_mov_b32_e32 v9, v1
	v_mov_b32_e32 v10, v1
	v_mov_b32_e32 v11, v1
	v_mov_b32_e32 v12, v1
	v_mov_b32_e32 v13, v1
	v_mov_b64_e32 v[32:33], v[14:15]
	s_or_b32 s7, s34, 3
	s_or_b32 s5, s20, 31
	s_add_i32 s13, s20, s13
	s_lshl_b32 s20, s8, 8
	s_lshl_b32 s8, s8, 6
	v_mov_b64_e32 v[30:31], v[12:13]
	v_mov_b64_e32 v[28:29], v[10:11]
	v_mov_b64_e32 v[26:27], v[8:9]
	v_mov_b64_e32 v[24:25], v[6:7]
	v_mov_b64_e32 v[22:23], v[4:5]
	v_mov_b64_e32 v[20:21], v[2:3]
	v_mov_b64_e32 v[18:19], v[0:1]
	v_mov_b64_e32 v[16:17], v[14:15]
	s_sub_i32 s7, s7, s1
	s_sub_i32 s30, s30, s8
	s_mov_b32 s31, 0
	s_movk_i32 s34, 0xfc00
	v_mov_b64_e32 v[14:15], v[12:13]
	v_mov_b64_e32 v[12:13], v[10:11]
	v_mov_b64_e32 v[10:11], v[8:9]
	v_mov_b64_e32 v[8:9], v[6:7]
	v_mov_b64_e32 v[6:7], v[4:5]
	v_mov_b64_e32 v[4:5], v[2:3]
	v_mov_b64_e32 v[2:3], v[0:1]
	s_waitcnt vmcnt(0) lgkmcnt(0)
	s_barrier
	s_cmp_lt_u32 s4, 0x1000
	s_cbranch_scc1 .LBB0_400
	s_setprio 1
	s_branch .LBB0_400

.LBB0_420:
	s_setprio 0
	v_add_f32_e32 v254, v226, v227
	v_add_f32_e32 v255, v228, v229
	v_add_f32_e32 v254, v254, v230
	v_add_f32_e32 v255, v255, v231
	v_add_f32_e32 v254, v254, v232
	v_add_f32_e32 v255, v255, v233
	v_add_f32_e32 v254, v254, v234
	v_add_f32_e32 v255, v255, v235
	v_add_f32_e32 v254, v254, v236
	v_add_f32_e32 v255, v255, v237
	v_add_f32_e32 v254, v254, v238
	v_add_f32_e32 v255, v255, v239
	v_add_f32_e32 v254, v254, v240
	v_add_f32_e32 v255, v255, v241
	v_add_f32_e32 v254, v254, v242
	v_add_f32_e32 v255, v255, v243
	v_add_f32_e32 v254, v254, v244
	v_add_f32_e32 v255, v255, v245
	v_add_f32_e32 v254, v254, v246
	v_add_f32_e32 v255, v255, v247
	v_add_f32_e32 v254, v254, v248
	v_add_f32_e32 v255, v255, v249
	v_add_f32_e32 v254, v254, v166
	v_add_f32_e32 v255, v255, v167
	v_add_f32_e32 v254, v254, v168
	v_add_f32_e32 v255, v255, v169
	v_add_f32_e32 v254, v254, v170
	v_add_f32_e32 v255, v255, v171
	v_add_f32_e32 v254, v254, v172
	v_add_f32_e32 v255, v255, v173
	v_add_f32_e32 v254, v254, v255
	v_add_f32_e32 v143, v143, v254
	v_xor_b32_e32 v0, 32, v187
	v_cmp_lt_i32_e32 vcc, v0, v189
	s_cmp_lg_u64 s[40:41], 0
	s_nop 0
	v_cndmask_b32_e32 v0, v187, v0, vcc
	v_lshlrev_b32_e32 v0, 2, v0
	ds_bpermute_b32 v0, v0, v143
	s_waitcnt lgkmcnt(0)
	v_add_f32_e32 v34, v143, v0
	v_div_scale_f32 v0, s[4:5], v34, v34, 1.0
	v_rcp_f32_e32 v35, v0
	s_nop 0
	v_fma_f32 v36, -v0, v35, 1.0
	v_fmac_f32_e32 v35, v36, v35
	v_div_scale_f32 v36, vcc, 1.0, v34, 1.0
	v_mul_f32_e32 v37, v36, v35
	v_fma_f32 v38, -v0, v37, v36
	v_fmac_f32_e32 v37, v38, v35
	v_fma_f32 v0, -v0, v37, v36
	v_div_fmas_f32 v0, v0, v35, v37
	v_mad_u64_u32 v[36:37], s[4:5], v122, s46, 0
	v_mad_i32_i24 v37, v123, s46, v37
	v_div_fixup_f32 v35, v0, v34, 1.0
	v_lshl_add_u64 v[36:37], v[36:37], 1, s[44:45]
	v_lshlrev_b32_e32 v0, 1, v125
	v_lshl_add_u64 v[36:37], v[36:37], 0, v[0:1]
	s_cselect_b64 s[4:5], -1, 0
	s_and_b64 s[4:5], s[4:5], s[36:37]
	v_lshl_add_u64 v[36:37], v[36:37], 0, v[0:1]
	v_mul_f32_e32 v182, v18, v35
	v_mul_f32_e32 v183, v19, v35
	v_cvt_pk_bf16_f32 v196, v182, v183
	v_mul_f32_e32 v182, v20, v35
	v_mul_f32_e32 v183, v21, v35
	v_cvt_pk_bf16_f32 v197, v182, v183
	v_mul_f32_e32 v182, v22, v35
	v_mul_f32_e32 v183, v23, v35
	v_cvt_pk_bf16_f32 v198, v182, v183
	v_mul_f32_e32 v182, v24, v35
	v_mul_f32_e32 v183, v25, v35
	v_cvt_pk_bf16_f32 v199, v182, v183
	v_mul_f32_e32 v182, v26, v35
	v_mul_f32_e32 v183, v27, v35
	v_cvt_pk_bf16_f32 v200, v182, v183
	v_mul_f32_e32 v182, v28, v35
	v_mul_f32_e32 v183, v29, v35
	v_cvt_pk_bf16_f32 v201, v182, v183
	v_mul_f32_e32 v182, v30, v35
	v_mul_f32_e32 v183, v31, v35
	v_cvt_pk_bf16_f32 v202, v182, v183
	v_mul_f32_e32 v182, v32, v35
	v_mul_f32_e32 v183, v33, v35
	v_cvt_pk_bf16_f32 v203, v182, v183
	v_mul_f32_e32 v182, v2, v35
	v_mul_f32_e32 v183, v3, v35
	v_cvt_pk_bf16_f32 v204, v182, v183
	v_mul_f32_e32 v182, v4, v35
	v_mul_f32_e32 v183, v5, v35
	v_cvt_pk_bf16_f32 v205, v182, v183
	v_mul_f32_e32 v182, v6, v35
	v_mul_f32_e32 v183, v7, v35
	v_cvt_pk_bf16_f32 v206, v182, v183
	v_mul_f32_e32 v182, v8, v35
	v_mul_f32_e32 v183, v9, v35
	v_cvt_pk_bf16_f32 v207, v182, v183
	v_mul_f32_e32 v182, v10, v35
	v_mul_f32_e32 v183, v11, v35
	v_cvt_pk_bf16_f32 v208, v182, v183
	v_mul_f32_e32 v182, v12, v35
	v_mul_f32_e32 v183, v13, v35
	v_cvt_pk_bf16_f32 v209, v182, v183
	v_mul_f32_e32 v182, v14, v35
	v_mul_f32_e32 v183, v15, v35
	v_cvt_pk_bf16_f32 v210, v182, v183
	v_mul_f32_e32 v182, v16, v35
	v_mul_f32_e32 v183, v17, v35
	v_cvt_pk_bf16_f32 v211, v182, v183
	s_nop 1
	v_permlane32_swap_b32_e32 v196, v198
	v_permlane32_swap_b32_e32 v197, v199
	v_permlane32_swap_b32_e32 v200, v202
	v_permlane32_swap_b32_e32 v201, v203
	v_permlane32_swap_b32_e32 v204, v206
	v_permlane32_swap_b32_e32 v205, v207
	v_permlane32_swap_b32_e32 v208, v210
	v_permlane32_swap_b32_e32 v209, v211
	global_store_dwordx4 v[36:37], v[196:199], off
	global_store_dwordx4 v[36:37], v[200:203], off offset:32
	global_store_dwordx4 v[36:37], v[204:207], off offset:64
	global_store_dwordx4 v[36:37], v[208:211], off offset:96
	s_and_saveexec_b64 s[16:17], s[4:5]
	s_cbranch_execz .LBB0_363
	v_log_f32_e32 v0, v34
	v_mad_u64_u32 v[2:3], s[4:5], v122, s42, 0
	v_mad_i32_i24 v3, v123, s42, v3
	v_add_f32_e32 v0, v140, v0
	v_mul_f32_e32 v0, 0x3f317218, v0
	v_lshl_add_u64 v[2:3], v[2:3], 2, s[40:41]
	global_store_dword v[2:3], v0, off
	s_branch .LBB0_363
